# mix_out: S5 GLU gate + per-token sum of squares with the 16 wave reductions interleaved (10 LDS round trips instead of 80); HGRN output epilogue operands loaded in one batch
# speedup vs baseline: 1.0367x; 1.0065x over previous
.LBB0_1334:
	v_mul_f32_e32 v42, v17, v17
	v_fmac_f32_e32 v42, v16, v16
	v_fmac_f32_e32 v42, v18, v18
	v_fmac_f32_e32 v42, v19, v19
	v_fmac_f32_e32 v42, v20, v20
	v_fmac_f32_e32 v42, v21, v21
	v_fmac_f32_e32 v42, v22, v22
	v_fmac_f32_e32 v42, v23, v23
	v_fmac_f32_e32 v42, v24, v24
	v_fmac_f32_e32 v42, v25, v25
	v_fmac_f32_e32 v42, v26, v26
	v_fmac_f32_e32 v42, v27, v27
	v_fmac_f32_e32 v42, v28, v28
	v_fmac_f32_e32 v42, v29, v29
	v_fmac_f32_e32 v42, v30, v30
	v_fmac_f32_e32 v42, v31, v31
	v_fmac_f32_e32 v42, v0, v0
	v_fmac_f32_e32 v42, v1, v1
	v_fmac_f32_e32 v42, v2, v2
	v_fmac_f32_e32 v42, v3, v3
	v_fmac_f32_e32 v42, v4, v4
	v_fmac_f32_e32 v42, v5, v5
	v_pk_mul_f32 v[40:41], v[6:7], v[6:7]
	v_pk_mul_f32 v[38:39], v[8:9], v[8:9]
	v_add_f32_e32 v40, v40, v42
	v_add_f32_e32 v40, v41, v40
	v_add_f32_e32 v38, v38, v40
	v_pk_mul_f32 v[36:37], v[10:11], v[10:11]
	v_add_f32_e32 v38, v39, v38
	v_add_f32_e32 v36, v36, v38
	v_pk_mul_f32 v[34:35], v[12:13], v[12:13]
	v_add_f32_e32 v36, v37, v36
	v_add_f32_e32 v34, v34, v36
	v_pk_mul_f32 v[32:33], v[14:15], v[14:15]
	v_add_f32_e32 v34, v35, v34
	v_add_f32_e32 v32, v32, v34
	v_and_b32_e32 v34, 64, v244
	v_add_f32_e32 v32, v33, v32
	v_xor_b32_e32 v33, 32, v244
	v_add_u32_e32 v34, 64, v34
	v_cmp_lt_i32_e32 vcc, v33, v34
	ds_read_b64 v[34:35], v229 offset:63760
	ds_read_b64 v[38:39], v229 offset:63696
	v_cndmask_b32_e32 v33, v244, v33, vcc
	v_lshlrev_b32_e32 v33, 2, v33
	ds_bpermute_b32 v33, v33, v32
	v_readlane_b32 s0, v255, 27
	v_readlane_b32 s1, v255, 28
	s_lshl_b64 s[0:1], s[0:1], 2
	v_lshlrev_b32_e32 v228, 2, v77
	s_waitcnt lgkmcnt(0)
	v_add_f32_e32 v32, v32, v33
	v_fmamk_f32 v32, v32, 0x3c800000, v230
	v_cmp_gt_f32_e32 vcc, s92, v32
	v_mul_f32_e32 v33, 0x4b800000, v32
	v_lshl_add_u64 v[38:39], v[38:39], 0, s[0:1]
	v_cndmask_b32_e32 v32, v32, v33, vcc
	v_rsq_f32_e32 v32, v32
	s_mov_b64 s[0:1], 0x1400
	s_movk_i32 s2, 0x1000
	v_lshl_add_u64 v[38:39], v[38:39], 0, v[66:67]
	v_mul_f32_e32 v33, 0x45800000, v32
	v_cndmask_b32_e32 v40, v32, v33, vcc
	v_or_b32_e32 v32, s70, v78
	v_ashrrev_i32_e32 v33, 31, v32
	v_lshlrev_b64 v[36:37], 13, v[32:33]
	v_lshl_add_u64 v[36:37], s[78:79], 0, v[36:37]
	v_lshlrev_b64 v[32:33], 11, v[32:33]
	v_lshl_add_u64 v[36:37], v[36:37], 0, v[66:67]
	v_lshl_add_u64 v[32:33], v[34:35], 0, v[32:33]
	v_lshl_add_u64 v[46:47], v[64:65], 1, v[32:33]
	v_lshl_add_u64 v[32:33], v[36:37], 0, v[228:229]
	v_lshl_add_u64 v[42:43], v[32:33], 0, s[0:1]
	v_add_co_u32_e32 v32, vcc, s2, v32
	v_lshl_add_u64 v[44:45], v[38:39], 0, v[228:229]
	s_nop 0
	v_addc_co_u32_e32 v33, vcc, 0, v33, vcc
	global_load_dwordx4 v[136:139], v[42:43], off
	global_load_dwordx4 v[140:143], v[44:45], off offset:1024
	global_load_dwordx4 v[144:147], v[42:43], off offset:32
	global_load_dwordx4 v[148:151], v[44:45], off offset:1056
	global_load_dwordx4 v[152:155], v[42:43], off offset:64
	global_load_dwordx4 v[156:159], v[44:45], off offset:1088
	global_load_dwordx4 v[160:163], v[42:43], off offset:96
	global_load_dwordx4 v[164:167], v[44:45], off offset:1120
	global_load_dwordx4 v[168:171], v[42:43], off offset:128
	global_load_dwordx4 v[172:175], v[44:45], off offset:1152
	global_load_dwordx4 v[176:179], v[42:43], off offset:160
	global_load_dwordx4 v[180:183], v[44:45], off offset:1184
	global_load_dwordx4 v[184:187], v[42:43], off offset:192
	global_load_dwordx4 v[188:191], v[44:45], off offset:1216
	global_load_dwordx4 v[192:195], v[42:43], off offset:224
	global_load_dwordx4 v[196:199], v[44:45], off offset:1248
	s_waitcnt vmcnt(14)
	v_mov_b32_e32 v32, v136
	v_mov_b32_e32 v33, v137
	v_mov_b32_e32 v34, v138
	v_mov_b32_e32 v35, v139
	v_lshlrev_b32_e32 v228, 1, v77
	v_mov_b32_e32 v36, v140
	v_mov_b32_e32 v37, v141
	v_mov_b32_e32 v38, v142
	v_mov_b32_e32 v39, v143
	s_mov_b32 s0, 0x7060302
	s_mov_b64 s[4:5], 0x4ad4200
	s_mov_b32 s1, 0x4ad4000
	v_readlane_b32 s3, v255, 32
	v_mul_f32_e32 v41, 0xbfb8aa3b, v32
	v_exp_f32_e32 v41, v41
	s_nop 0
	v_add_f32_e32 v41, 1.0, v41
	v_rcp_f32_e32 v48, v41
	v_mul_f32_e32 v41, 0xbfb8aa3b, v33
	v_exp_f32_e32 v41, v41
	s_nop 0
	v_add_f32_e32 v41, 1.0, v41
	v_rcp_f32_e32 v49, v41
	v_pk_mul_f32 v[16:17], v[16:17], v[40:41] op_sel_hi:[1,0]
	v_pk_mul_f32 v[18:19], v[18:19], v[40:41] op_sel_hi:[1,0]
	v_pk_mul_f32 v[16:17], v[36:37], v[16:17]
	v_pk_mul_f32 v[32:33], v[32:33], v[48:49]
	v_pk_mul_f32 v[18:19], v[38:39], v[18:19]
	v_pk_mul_f32 v[16:17], v[32:33], v[16:17]
	v_mul_f32_e32 v32, 0xbfb8aa3b, v34
	v_mul_f32_e32 v33, 0xbfb8aa3b, v35
	v_exp_f32_e32 v32, v32
	v_exp_f32_e32 v33, v33
	v_pk_mul_f32 v[20:21], v[20:21], v[40:41] op_sel_hi:[1,0]
	v_pk_mul_f32 v[22:23], v[22:23], v[40:41] op_sel_hi:[1,0]
	v_add_f32_e32 v32, 1.0, v32
	v_add_f32_e32 v33, 1.0, v33
	v_rcp_f32_e32 v32, v32
	v_rcp_f32_e32 v33, v33
	v_pk_mul_f32 v[24:25], v[24:25], v[40:41] op_sel_hi:[1,0]
	v_pk_mul_f32 v[28:29], v[28:29], v[40:41] op_sel_hi:[1,0]
	v_pk_mul_f32 v[0:1], v[0:1], v[40:41] op_sel_hi:[1,0]
	v_pk_mul_f32 v[32:33], v[34:35], v[32:33]
	v_bfe_u32 v34, v17, 16, 1
	v_pk_mul_f32 v[18:19], v[32:33], v[18:19]
	v_bfe_u32 v35, v16, 16, 1
	v_bfe_u32 v32, v19, 16, 1
	v_bfe_u32 v33, v18, 16, 1
	v_add3_u32 v16, v16, v35, s89
	v_add3_u32 v17, v17, v34, s89
	v_add3_u32 v18, v18, v33, s89
	v_add3_u32 v19, v19, v32, s89
	v_lshl_add_u64 v[32:33], v[46:47], 0, v[228:229]
	v_perm_b32 v19, v19, v18, s0
	v_perm_b32 v18, v17, v16, s0
	v_lshl_add_u64 v[16:17], v[32:33], 0, s[4:5]
	v_add_co_u32_e32 v32, vcc, s1, v32
	v_pk_mul_f32 v[2:3], v[2:3], v[40:41] op_sel_hi:[1,0]
	s_nop 0
	v_addc_co_u32_e32 v33, vcc, 0, v33, vcc
	global_store_dwordx2 v[32:33], v[18:19], off offset:512
	s_waitcnt vmcnt(13)
	v_mov_b32_e32 v32, v144
	v_mov_b32_e32 v33, v145
	v_mov_b32_e32 v34, v146
	v_mov_b32_e32 v35, v147
	s_nop 0
	v_mov_b32_e32 v36, v148
	v_mov_b32_e32 v37, v149
	v_mov_b32_e32 v38, v150
	v_mov_b32_e32 v39, v151
	v_pk_mul_f32 v[4:5], v[4:5], v[40:41] op_sel_hi:[1,0]
	v_pk_mul_f32 v[6:7], v[6:7], v[40:41] op_sel_hi:[1,0]
	v_pk_mul_f32 v[8:9], v[8:9], v[40:41] op_sel_hi:[1,0]
	v_mul_f32_e32 v18, 0xbfb8aa3b, v32
	v_mul_f32_e32 v19, 0xbfb8aa3b, v33
	v_exp_f32_e32 v18, v18
	v_exp_f32_e32 v19, v19
	v_pk_mul_f32 v[20:21], v[36:37], v[20:21]
	v_pk_mul_f32 v[22:23], v[38:39], v[22:23]
	v_add_f32_e32 v18, 1.0, v18
	v_add_f32_e32 v19, 1.0, v19
	v_rcp_f32_e32 v18, v18
	v_rcp_f32_e32 v19, v19
	s_nop 0
	v_pk_mul_f32 v[18:19], v[32:33], v[18:19]
	s_nop 0
	v_pk_mul_f32 v[18:19], v[20:21], v[18:19]
	v_mul_f32_e32 v20, 0xbfb8aa3b, v34
	v_mul_f32_e32 v21, 0xbfb8aa3b, v35
	v_exp_f32_e32 v20, v20
	v_exp_f32_e32 v21, v21
	v_bfe_u32 v32, v19, 16, 1
	v_bfe_u32 v33, v18, 16, 1
	v_add_f32_e32 v20, 1.0, v20
	v_add_f32_e32 v21, 1.0, v21
	v_rcp_f32_e32 v20, v20
	v_rcp_f32_e32 v21, v21
	v_add3_u32 v18, v18, v33, s89
	v_add3_u32 v32, v19, v32, s89
	v_perm_b32 v18, v32, v18, s0
	v_pk_mul_f32 v[20:21], v[34:35], v[20:21]
	s_nop 0
	v_pk_mul_f32 v[20:21], v[22:23], v[20:21]
	s_nop 0
	v_bfe_u32 v22, v21, 16, 1
	v_bfe_u32 v23, v20, 16, 1
	v_add3_u32 v19, v20, v23, s89
	v_add3_u32 v20, v21, v22, s89
	v_perm_b32 v19, v20, v19, s0
	global_store_dwordx2 v[16:17], v[18:19], off offset:16
	s_waitcnt vmcnt(12)
	v_mov_b32_e32 v18, v152
	v_mov_b32_e32 v19, v153
	v_mov_b32_e32 v20, v154
	v_mov_b32_e32 v21, v155
	s_nop 0
	v_mov_b32_e32 v32, v156
	v_mov_b32_e32 v33, v157
	v_mov_b32_e32 v34, v158
	v_mov_b32_e32 v35, v159
	v_mul_f32_e32 v22, 0xbfb8aa3b, v18
	v_mul_f32_e32 v23, 0xbfb8aa3b, v19
	v_exp_f32_e32 v22, v22
	v_exp_f32_e32 v23, v23
	v_pk_mul_f32 v[24:25], v[24:25], v[32:33]
	v_add_f32_e32 v22, 1.0, v22
	v_add_f32_e32 v23, 1.0, v23
	v_rcp_f32_e32 v22, v22
	v_rcp_f32_e32 v23, v23
	s_nop 0
	v_pk_mul_f32 v[18:19], v[18:19], v[22:23]
	v_mul_f32_e32 v22, 0xbfb8aa3b, v20
	v_mul_f32_e32 v23, 0xbfb8aa3b, v21
	v_exp_f32_e32 v22, v22
	v_exp_f32_e32 v23, v23
	v_pk_mul_f32 v[18:19], v[24:25], v[18:19]
	v_pk_mul_f32 v[24:25], v[26:27], v[40:41] op_sel_hi:[1,0]
	v_add_f32_e32 v22, 1.0, v22
	v_add_f32_e32 v23, 1.0, v23
	v_rcp_f32_e32 v22, v22
	v_rcp_f32_e32 v23, v23
	v_pk_mul_f32 v[24:25], v[24:25], v[34:35]
	v_pk_mul_f32 v[20:21], v[20:21], v[22:23]
	s_nop 0
	v_pk_mul_f32 v[20:21], v[24:25], v[20:21]
	v_bfe_u32 v24, v19, 16, 1
	v_bfe_u32 v22, v21, 16, 1
	v_bfe_u32 v23, v20, 16, 1
	v_bfe_u32 v25, v18, 16, 1
	v_add3_u32 v18, v18, v25, s89
	v_add3_u32 v24, v19, v24, s89
	v_add3_u32 v19, v20, v23, s89
	v_add3_u32 v20, v21, v22, s89
	v_perm_b32 v19, v20, v19, s0
	v_perm_b32 v18, v24, v18, s0
	global_store_dwordx2 v[16:17], v[18:19], off offset:32
	s_waitcnt vmcnt(11)
	v_mov_b32_e32 v18, v160
	v_mov_b32_e32 v19, v161
	v_mov_b32_e32 v20, v162
	v_mov_b32_e32 v21, v163
	s_nop 0
	v_mov_b32_e32 v22, v164
	v_mov_b32_e32 v23, v165
	v_mov_b32_e32 v24, v166
	v_mov_b32_e32 v25, v167
	v_mul_f32_e32 v26, 0xbfb8aa3b, v18
	v_mul_f32_e32 v27, 0xbfb8aa3b, v19
	v_exp_f32_e32 v26, v26
	v_exp_f32_e32 v27, v27
	v_pk_mul_f32 v[22:23], v[28:29], v[22:23]
	v_add_f32_e32 v26, 1.0, v26
	v_add_f32_e32 v27, 1.0, v27
	v_rcp_f32_e32 v26, v26
	v_rcp_f32_e32 v27, v27
	s_nop 0
	v_pk_mul_f32 v[18:19], v[18:19], v[26:27]
	s_nop 0
	v_pk_mul_f32 v[18:19], v[22:23], v[18:19]
	v_mul_f32_e32 v22, 0xbfb8aa3b, v20
	v_mul_f32_e32 v23, 0xbfb8aa3b, v21
	v_exp_f32_e32 v22, v22
	v_exp_f32_e32 v23, v23
	v_pk_mul_f32 v[26:27], v[30:31], v[40:41] op_sel_hi:[1,0]
	v_add_f32_e32 v22, 1.0, v22
	v_add_f32_e32 v23, 1.0, v23
	v_rcp_f32_e32 v22, v22
	v_rcp_f32_e32 v23, v23
	v_pk_mul_f32 v[24:25], v[26:27], v[24:25]
	v_pk_mul_f32 v[20:21], v[20:21], v[22:23]
	s_nop 0
	v_pk_mul_f32 v[20:21], v[24:25], v[20:21]
	v_bfe_u32 v24, v19, 16, 1
	v_bfe_u32 v22, v21, 16, 1
	v_bfe_u32 v23, v20, 16, 1
	v_bfe_u32 v25, v18, 16, 1
	v_add3_u32 v18, v18, v25, s89
	v_add3_u32 v24, v19, v24, s89
	v_add3_u32 v19, v20, v23, s89
	v_add3_u32 v20, v21, v22, s89
	v_perm_b32 v19, v20, v19, s0
	v_perm_b32 v18, v24, v18, s0
	global_store_dwordx2 v[16:17], v[18:19], off offset:48
	s_waitcnt vmcnt(10)
	v_mov_b32_e32 v18, v168
	v_mov_b32_e32 v19, v169
	v_mov_b32_e32 v20, v170
	v_mov_b32_e32 v21, v171
	s_nop 0
	v_mov_b32_e32 v22, v172
	v_mov_b32_e32 v23, v173
	v_mov_b32_e32 v24, v174
	v_mov_b32_e32 v25, v175
	v_mul_f32_e32 v26, 0xbfb8aa3b, v18
	v_mul_f32_e32 v27, 0xbfb8aa3b, v19
	v_exp_f32_e32 v26, v26
	v_exp_f32_e32 v27, v27
	v_pk_mul_f32 v[0:1], v[0:1], v[22:23]
	v_pk_mul_f32 v[2:3], v[2:3], v[24:25]
	v_add_f32_e32 v26, 1.0, v26
	v_add_f32_e32 v27, 1.0, v27
	v_rcp_f32_e32 v26, v26
	v_rcp_f32_e32 v27, v27
	s_nop 0
	v_pk_mul_f32 v[18:19], v[18:19], v[26:27]
	s_nop 0
	v_pk_mul_f32 v[0:1], v[0:1], v[18:19]
	v_mul_f32_e32 v18, 0xbfb8aa3b, v20
	v_mul_f32_e32 v19, 0xbfb8aa3b, v21
	v_exp_f32_e32 v18, v18
	v_exp_f32_e32 v19, v19
	v_add_f32_e32 v18, 1.0, v18
	v_add_f32_e32 v19, 1.0, v19
	v_rcp_f32_e32 v18, v18
	v_rcp_f32_e32 v19, v19
	s_nop 0
	v_pk_mul_f32 v[18:19], v[20:21], v[18:19]
	s_nop 0
	v_pk_mul_f32 v[2:3], v[2:3], v[18:19]
	v_bfe_u32 v20, v1, 16, 1
	v_bfe_u32 v18, v3, 16, 1
	v_bfe_u32 v19, v2, 16, 1
	v_bfe_u32 v21, v0, 16, 1
	v_add3_u32 v0, v0, v21, s89
	v_add3_u32 v20, v1, v20, s89
	v_add3_u32 v1, v2, v19, s89
	v_add3_u32 v2, v3, v18, s89
	v_perm_b32 v1, v2, v1, s0
	v_perm_b32 v0, v20, v0, s0
	global_store_dwordx2 v[16:17], v[0:1], off offset:64
	s_waitcnt vmcnt(9)
	v_mov_b32_e32 v0, v176
	v_mov_b32_e32 v1, v177
	v_mov_b32_e32 v2, v178
	v_mov_b32_e32 v3, v179
	s_nop 0
	v_mov_b32_e32 v18, v180
	v_mov_b32_e32 v19, v181
	v_mov_b32_e32 v20, v182
	v_mov_b32_e32 v21, v183
	v_mul_f32_e32 v22, 0xbfb8aa3b, v0
	v_mul_f32_e32 v23, 0xbfb8aa3b, v1
	v_exp_f32_e32 v22, v22
	v_exp_f32_e32 v23, v23
	v_pk_mul_f32 v[4:5], v[4:5], v[18:19]
	v_pk_mul_f32 v[6:7], v[6:7], v[20:21]
	v_add_f32_e32 v22, 1.0, v22
	v_add_f32_e32 v23, 1.0, v23
	v_rcp_f32_e32 v22, v22
	v_rcp_f32_e32 v23, v23
	s_nop 0
	v_pk_mul_f32 v[0:1], v[0:1], v[22:23]
	s_nop 0
	v_pk_mul_f32 v[0:1], v[4:5], v[0:1]
	v_mul_f32_e32 v4, 0xbfb8aa3b, v2
	v_mul_f32_e32 v5, 0xbfb8aa3b, v3
	v_exp_f32_e32 v4, v4
	v_exp_f32_e32 v5, v5
	v_add_f32_e32 v4, 1.0, v4
	v_add_f32_e32 v5, 1.0, v5
	v_rcp_f32_e32 v4, v4
	v_rcp_f32_e32 v5, v5
	s_nop 0
	v_pk_mul_f32 v[2:3], v[2:3], v[4:5]
	s_nop 0
	v_pk_mul_f32 v[2:3], v[6:7], v[2:3]
	v_bfe_u32 v6, v1, 16, 1
	v_bfe_u32 v4, v3, 16, 1
	v_bfe_u32 v5, v2, 16, 1
	v_bfe_u32 v7, v0, 16, 1
	v_add3_u32 v0, v0, v7, s89
	v_add3_u32 v6, v1, v6, s89
	v_add3_u32 v1, v2, v5, s89
	v_add3_u32 v2, v3, v4, s89
	v_perm_b32 v1, v2, v1, s0
	v_perm_b32 v0, v6, v0, s0
	global_store_dwordx2 v[16:17], v[0:1], off offset:80
	s_waitcnt vmcnt(8)
	v_mov_b32_e32 v0, v184
	v_mov_b32_e32 v1, v185
	v_mov_b32_e32 v2, v186
	v_mov_b32_e32 v3, v187
	s_nop 0
	v_mov_b32_e32 v4, v188
	v_mov_b32_e32 v5, v189
	v_mov_b32_e32 v6, v190
	v_mov_b32_e32 v7, v191
	v_mul_f32_e32 v18, 0xbfb8aa3b, v0
	v_mul_f32_e32 v19, 0xbfb8aa3b, v1
	v_exp_f32_e32 v18, v18
	v_exp_f32_e32 v19, v19
	v_pk_mul_f32 v[4:5], v[8:9], v[4:5]
	v_pk_mul_f32 v[8:9], v[10:11], v[40:41] op_sel_hi:[1,0]
	v_add_f32_e32 v18, 1.0, v18
	v_add_f32_e32 v19, 1.0, v19
	v_rcp_f32_e32 v18, v18
	v_rcp_f32_e32 v19, v19
	v_pk_mul_f32 v[6:7], v[8:9], v[6:7]
	v_pk_mul_f32 v[10:11], v[12:13], v[40:41] op_sel_hi:[1,0]
	v_pk_mul_f32 v[0:1], v[0:1], v[18:19]
	s_nop 0
	v_pk_mul_f32 v[0:1], v[4:5], v[0:1]
	v_mul_f32_e32 v4, 0xbfb8aa3b, v2
	v_mul_f32_e32 v5, 0xbfb8aa3b, v3
	v_exp_f32_e32 v4, v4
	v_exp_f32_e32 v5, v5
	v_add_f32_e32 v4, 1.0, v4
	v_add_f32_e32 v5, 1.0, v5
	v_rcp_f32_e32 v4, v4
	v_rcp_f32_e32 v5, v5
	s_nop 0
	v_pk_mul_f32 v[2:3], v[2:3], v[4:5]
	s_nop 0
	v_pk_mul_f32 v[2:3], v[6:7], v[2:3]
	v_bfe_u32 v6, v1, 16, 1
	v_bfe_u32 v4, v3, 16, 1
	v_bfe_u32 v5, v2, 16, 1
	v_bfe_u32 v7, v0, 16, 1
	v_add3_u32 v0, v0, v7, s89
	v_add3_u32 v6, v1, v6, s89
	v_add3_u32 v1, v2, v5, s89
	v_add3_u32 v2, v3, v4, s89
	v_perm_b32 v1, v2, v1, s0
	v_perm_b32 v0, v6, v0, s0
	global_store_dwordx2 v[16:17], v[0:1], off offset:96
	s_waitcnt vmcnt(7)
	v_mov_b32_e32 v0, v192
	v_mov_b32_e32 v1, v193
	v_mov_b32_e32 v2, v194
	v_mov_b32_e32 v3, v195
	s_nop 0
	v_mov_b32_e32 v4, v196
	v_mov_b32_e32 v5, v197
	v_mov_b32_e32 v6, v198
	v_mov_b32_e32 v7, v199
	v_mul_f32_e32 v8, 0xbfb8aa3b, v0
	v_mul_f32_e32 v9, 0xbfb8aa3b, v1
	v_exp_f32_e32 v8, v8
	v_exp_f32_e32 v9, v9
	v_pk_mul_f32 v[4:5], v[10:11], v[4:5]
	v_add_f32_e32 v8, 1.0, v8
	v_add_f32_e32 v9, 1.0, v9
	v_rcp_f32_e32 v8, v8
	v_rcp_f32_e32 v9, v9
	s_nop 0
	v_pk_mul_f32 v[0:1], v[0:1], v[8:9]
	s_nop 0
	v_pk_mul_f32 v[0:1], v[4:5], v[0:1]
	v_mul_f32_e32 v4, 0xbfb8aa3b, v2
	v_mul_f32_e32 v5, 0xbfb8aa3b, v3
	v_exp_f32_e32 v4, v4
	v_exp_f32_e32 v5, v5
	v_pk_mul_f32 v[8:9], v[14:15], v[40:41] op_sel_hi:[1,0]
	v_add_f32_e32 v4, 1.0, v4
	v_add_f32_e32 v5, 1.0, v5
	v_rcp_f32_e32 v4, v4
	v_rcp_f32_e32 v5, v5
	v_pk_mul_f32 v[6:7], v[8:9], v[6:7]
	v_pk_mul_f32 v[2:3], v[2:3], v[4:5]
	s_nop 0
	v_pk_mul_f32 v[2:3], v[6:7], v[2:3]
	v_bfe_u32 v6, v1, 16, 1
	v_bfe_u32 v4, v3, 16, 1
	v_bfe_u32 v5, v2, 16, 1
	v_bfe_u32 v7, v0, 16, 1
	v_add3_u32 v0, v0, v7, s89
	v_add3_u32 v6, v1, v6, s89
	v_add3_u32 v1, v2, v5, s89
	v_add3_u32 v2, v3, v4, s89
	v_perm_b32 v1, v2, v1, s0
	v_perm_b32 v0, v6, v0, s0
	v_readlane_b32 s0, v255, 4
	s_add_i32 s3, s3, s0
	s_cmpk_gt_i32 s3, 0xff
	global_store_dwordx2 v[16:17], v[0:1], off offset:112
	s_cbranch_scc1 .LBB0_1469

.LBB0_1491:
	v_lshl_add_u64 v[206:207], v[38:39], 0, s[0:1]
	v_add_co_u32_e32 v208, vcc, s27, v206
	s_nop 1
	v_addc_co_u32_e32 v209, vcc, 0, v207, vcc
	v_lshl_add_u64 v[206:207], v[36:37], 0, s[0:1]
	v_add_co_u32_e32 v210, vcc, s27, v206
	s_nop 1
	v_addc_co_u32_e32 v211, vcc, 0, v207, vcc
	global_load_dwordx4 v[140:143], v[208:209], off
	global_load_dwordx4 v[144:147], v[210:211], off
	global_load_dwordx4 v[148:151], v[208:209], off offset:32
	global_load_dwordx4 v[152:155], v[210:211], off offset:32
	global_load_dwordx4 v[156:159], v[208:209], off offset:64
	global_load_dwordx4 v[160:163], v[210:211], off offset:64
	global_load_dwordx4 v[164:167], v[208:209], off offset:96
	global_load_dwordx4 v[168:171], v[210:211], off offset:96
	global_load_dwordx4 v[172:175], v[208:209], off offset:128
	global_load_dwordx4 v[176:179], v[210:211], off offset:128
	global_load_dwordx4 v[180:183], v[208:209], off offset:160
	global_load_dwordx4 v[184:187], v[210:211], off offset:160
	global_load_dwordx4 v[188:191], v[208:209], off offset:192
	global_load_dwordx4 v[192:195], v[210:211], off offset:192
	global_load_dwordx4 v[196:199], v[208:209], off offset:224
	global_load_dwordx4 v[200:203], v[210:211], off offset:224
	ds_read_b128 v[44:47], v42
	ds_read_b128 v[48:51], v42 offset:32
	ds_read_b128 v[52:55], v42 offset:64
	ds_read_b128 v[56:59], v42 offset:96
	ds_read_b128 v[60:63], v42 offset:128
	ds_read_b128 v[66:69], v42 offset:160
	ds_read_b128 v[70:73], v42 offset:192
	ds_read_b128 v[74:77], v42 offset:224
	v_add_u32_e32 v42, 0x100, v42
	s_add_u32 s0, s0, 0x100
	s_addc_u32 s1, s1, 0
	s_waitcnt vmcnt(14) lgkmcnt(7)
	v_mfma_f32_32x32x16_bf16 v[16:31], v[44:47], v[140:143], v[16:31]
	v_mfma_f32_32x32x16_bf16 v[0:15], v[44:47], v[144:147], v[0:15]
	s_waitcnt vmcnt(12) lgkmcnt(6)
	v_mfma_f32_32x32x16_bf16 v[16:31], v[48:51], v[148:151], v[16:31]
	v_mfma_f32_32x32x16_bf16 v[0:15], v[48:51], v[152:155], v[0:15]
	s_waitcnt vmcnt(10) lgkmcnt(5)
	v_mfma_f32_32x32x16_bf16 v[16:31], v[52:55], v[156:159], v[16:31]
	v_mfma_f32_32x32x16_bf16 v[0:15], v[52:55], v[160:163], v[0:15]
	s_waitcnt vmcnt(8) lgkmcnt(4)
	v_mfma_f32_32x32x16_bf16 v[16:31], v[56:59], v[164:167], v[16:31]
	v_mfma_f32_32x32x16_bf16 v[0:15], v[56:59], v[168:171], v[0:15]
	s_waitcnt vmcnt(6) lgkmcnt(3)
	v_mfma_f32_32x32x16_bf16 v[16:31], v[60:63], v[172:175], v[16:31]
	v_mfma_f32_32x32x16_bf16 v[0:15], v[60:63], v[176:179], v[0:15]
	s_waitcnt vmcnt(4) lgkmcnt(2)
	v_mfma_f32_32x32x16_bf16 v[16:31], v[66:69], v[180:183], v[16:31]
	v_mfma_f32_32x32x16_bf16 v[0:15], v[66:69], v[184:187], v[0:15]
	s_waitcnt vmcnt(2) lgkmcnt(1)
	v_mfma_f32_32x32x16_bf16 v[16:31], v[70:73], v[188:191], v[16:31]
	v_mfma_f32_32x32x16_bf16 v[0:15], v[70:73], v[192:195], v[0:15]
	s_waitcnt vmcnt(0) lgkmcnt(0)
	v_mfma_f32_32x32x16_bf16 v[16:31], v[74:77], v[196:199], v[16:31]
	v_mfma_f32_32x32x16_bf16 v[0:15], v[74:77], v[200:203], v[0:15]
	s_cmpk_eq_i32 s0, 0x200
	s_cbranch_scc0 .LBB0_1491
	s_nop 7
	s_nop 7
	v_lshlrev_b32_e32 v140, 1, v40
	v_lshl_add_u32 v140, v64, 1, v140
	v_mad_u32_u24 v141, v41, s24, v140
	v_and_b32_e32 v142, 64, v244
	v_add_u32_e32 v142, 64, v142
	v_xor_b32_e32 v148, 16, v244
	v_cmp_lt_i32_e32 vcc, v148, v142
	s_nop 1
	v_cndmask_b32_e32 v148, v244, v148, vcc
	v_lshlrev_b32_e32 v143, 2, v148
	v_xor_b32_e32 v148, 8, v244
	v_cmp_lt_i32_e32 vcc, v148, v142
	s_nop 1
	v_cndmask_b32_e32 v148, v244, v148, vcc
	v_lshlrev_b32_e32 v144, 2, v148
	v_xor_b32_e32 v148, 4, v244
	v_cmp_lt_i32_e32 vcc, v148, v142
	s_nop 1
	v_cndmask_b32_e32 v148, v244, v148, vcc
	v_lshlrev_b32_e32 v145, 2, v148
	v_xor_b32_e32 v148, 2, v244
	v_cmp_lt_i32_e32 vcc, v148, v142
	s_nop 1
	v_cndmask_b32_e32 v148, v244, v148, vcc
	v_lshlrev_b32_e32 v146, 2, v148
	v_xor_b32_e32 v148, 1, v244
	v_cmp_lt_i32_e32 vcc, v148, v142
	s_nop 1
	v_cndmask_b32_e32 v148, v244, v148, vcc
	v_lshlrev_b32_e32 v147, 2, v148
	v_lshlrev_b32_e32 v149, 2, v41
	v_lshlrev_b32_e32 v150, 7, v136
	v_lshl_add_u32 v151, v149, 2, v150
	v_mul_f32_e32 v16, 0xbfb8aa3b, v16
	v_mul_f32_e32 v17, 0xbfb8aa3b, v17
	v_mul_f32_e32 v18, 0xbfb8aa3b, v18
	v_mul_f32_e32 v19, 0xbfb8aa3b, v19
	v_mul_f32_e32 v20, 0xbfb8aa3b, v20
	v_mul_f32_e32 v21, 0xbfb8aa3b, v21
	v_mul_f32_e32 v22, 0xbfb8aa3b, v22
	v_mul_f32_e32 v23, 0xbfb8aa3b, v23
	v_mul_f32_e32 v24, 0xbfb8aa3b, v24
	v_mul_f32_e32 v25, 0xbfb8aa3b, v25
	v_mul_f32_e32 v26, 0xbfb8aa3b, v26
	v_mul_f32_e32 v27, 0xbfb8aa3b, v27
	v_mul_f32_e32 v28, 0xbfb8aa3b, v28
	v_mul_f32_e32 v29, 0xbfb8aa3b, v29
	v_mul_f32_e32 v30, 0xbfb8aa3b, v30
	v_mul_f32_e32 v31, 0xbfb8aa3b, v31
	v_mul_f32_e32 v0, 0xbfb8aa3b, v0
	v_mul_f32_e32 v1, 0xbfb8aa3b, v1
	v_mul_f32_e32 v2, 0xbfb8aa3b, v2
	v_mul_f32_e32 v3, 0xbfb8aa3b, v3
	v_mul_f32_e32 v4, 0xbfb8aa3b, v4
	v_mul_f32_e32 v5, 0xbfb8aa3b, v5
	v_mul_f32_e32 v6, 0xbfb8aa3b, v6
	v_mul_f32_e32 v7, 0xbfb8aa3b, v7
	v_mul_f32_e32 v8, 0xbfb8aa3b, v8
	v_mul_f32_e32 v9, 0xbfb8aa3b, v9
	v_mul_f32_e32 v10, 0xbfb8aa3b, v10
	v_mul_f32_e32 v11, 0xbfb8aa3b, v11
	v_mul_f32_e32 v12, 0xbfb8aa3b, v12
	v_mul_f32_e32 v13, 0xbfb8aa3b, v13
	v_mul_f32_e32 v14, 0xbfb8aa3b, v14
	v_mul_f32_e32 v15, 0xbfb8aa3b, v15
	v_exp_f32_e32 v16, v16
	v_exp_f32_e32 v17, v17
	v_exp_f32_e32 v18, v18
	v_exp_f32_e32 v19, v19
	v_exp_f32_e32 v20, v20
	v_exp_f32_e32 v21, v21
	v_exp_f32_e32 v22, v22
	v_exp_f32_e32 v23, v23
	v_exp_f32_e32 v24, v24
	v_exp_f32_e32 v25, v25
	v_exp_f32_e32 v26, v26
	v_exp_f32_e32 v27, v27
	v_exp_f32_e32 v28, v28
	v_exp_f32_e32 v29, v29
	v_exp_f32_e32 v30, v30
	v_exp_f32_e32 v31, v31
	v_exp_f32_e32 v0, v0
	v_exp_f32_e32 v1, v1
	v_exp_f32_e32 v2, v2
	v_exp_f32_e32 v3, v3
	v_exp_f32_e32 v4, v4
	v_exp_f32_e32 v5, v5
	v_exp_f32_e32 v6, v6
	v_exp_f32_e32 v7, v7
	v_exp_f32_e32 v8, v8
	v_exp_f32_e32 v9, v9
	v_exp_f32_e32 v10, v10
	v_exp_f32_e32 v11, v11
	v_exp_f32_e32 v12, v12
	v_exp_f32_e32 v13, v13
	v_exp_f32_e32 v14, v14
	v_exp_f32_e32 v15, v15
	v_add_f32_e32 v16, 1.0, v16
	v_add_f32_e32 v17, 1.0, v17
	v_add_f32_e32 v18, 1.0, v18
	v_add_f32_e32 v19, 1.0, v19
	v_add_f32_e32 v20, 1.0, v20
	v_add_f32_e32 v21, 1.0, v21
	v_add_f32_e32 v22, 1.0, v22
	v_add_f32_e32 v23, 1.0, v23
	v_add_f32_e32 v24, 1.0, v24
	v_add_f32_e32 v25, 1.0, v25
	v_add_f32_e32 v26, 1.0, v26
	v_add_f32_e32 v27, 1.0, v27
	v_add_f32_e32 v28, 1.0, v28
	v_add_f32_e32 v29, 1.0, v29
	v_add_f32_e32 v30, 1.0, v30
	v_add_f32_e32 v31, 1.0, v31
	v_add_f32_e32 v0, 1.0, v0
	v_add_f32_e32 v1, 1.0, v1
	v_add_f32_e32 v2, 1.0, v2
	v_add_f32_e32 v3, 1.0, v3
	v_add_f32_e32 v4, 1.0, v4
	v_add_f32_e32 v5, 1.0, v5
	v_add_f32_e32 v6, 1.0, v6
	v_add_f32_e32 v7, 1.0, v7
	v_add_f32_e32 v8, 1.0, v8
	v_add_f32_e32 v9, 1.0, v9
	v_add_f32_e32 v10, 1.0, v10
	v_add_f32_e32 v11, 1.0, v11
	v_add_f32_e32 v12, 1.0, v12
	v_add_f32_e32 v13, 1.0, v13
	v_add_f32_e32 v14, 1.0, v14
	v_add_f32_e32 v15, 1.0, v15
	v_rcp_f32_e32 v16, v16
	v_rcp_f32_e32 v17, v17
	v_rcp_f32_e32 v18, v18
	v_rcp_f32_e32 v19, v19
	v_rcp_f32_e32 v20, v20
	v_rcp_f32_e32 v21, v21
	v_rcp_f32_e32 v22, v22
	v_rcp_f32_e32 v23, v23
	v_rcp_f32_e32 v24, v24
	v_rcp_f32_e32 v25, v25
	v_rcp_f32_e32 v26, v26
	v_rcp_f32_e32 v27, v27
	v_rcp_f32_e32 v28, v28
	v_rcp_f32_e32 v29, v29
	v_rcp_f32_e32 v30, v30
	v_rcp_f32_e32 v31, v31
	v_rcp_f32_e32 v0, v0
	v_rcp_f32_e32 v1, v1
	v_rcp_f32_e32 v2, v2
	v_rcp_f32_e32 v3, v3
	v_rcp_f32_e32 v4, v4
	v_rcp_f32_e32 v5, v5
	v_rcp_f32_e32 v6, v6
	v_rcp_f32_e32 v7, v7
	v_rcp_f32_e32 v8, v8
	v_rcp_f32_e32 v9, v9
	v_rcp_f32_e32 v10, v10
	v_rcp_f32_e32 v11, v11
	v_rcp_f32_e32 v12, v12
	v_rcp_f32_e32 v13, v13
	v_rcp_f32_e32 v14, v14
	v_rcp_f32_e32 v15, v15
	ds_read_u16 v152, v141 offset:34816
	ds_read_u16 v153, v141 offset:34880
	ds_read_u16 v154, v141 offset:35344
	ds_read_u16 v155, v141 offset:35408
	ds_read_u16 v156, v141 offset:35872
	ds_read_u16 v157, v141 offset:35936
	ds_read_u16 v158, v141 offset:36400
	ds_read_u16 v159, v141 offset:36464
	s_waitcnt lgkmcnt(0)
	v_lshlrev_b32_e32 v152, 16, v152
	v_lshlrev_b32_e32 v153, 16, v153
	v_mul_f32_e32 v184, v16, v152
	v_mul_f32_e32 v185, v0, v153
	v_mul_f32_e32 v109, v185, v185
	v_fmac_f32_e32 v109, v184, v184
	v_lshlrev_b32_e32 v154, 16, v154
	v_lshlrev_b32_e32 v155, 16, v155
	v_mul_f32_e32 v186, v17, v154
	v_mul_f32_e32 v187, v1, v155
	v_mul_f32_e32 v110, v187, v187
	v_fmac_f32_e32 v110, v186, v186
	v_lshlrev_b32_e32 v156, 16, v156
	v_lshlrev_b32_e32 v157, 16, v157
	v_mul_f32_e32 v188, v18, v156
	v_mul_f32_e32 v189, v2, v157
	v_mul_f32_e32 v111, v189, v189
	v_fmac_f32_e32 v111, v188, v188
	v_lshlrev_b32_e32 v158, 16, v158
	v_lshlrev_b32_e32 v159, 16, v159
	v_mul_f32_e32 v190, v19, v158
	v_mul_f32_e32 v191, v3, v159
	v_mul_f32_e32 v112, v191, v191
	v_fmac_f32_e32 v112, v190, v190
	ds_read_u16 v160, v141 offset:39040
	ds_read_u16 v161, v141 offset:39104
	ds_read_u16 v162, v141 offset:39568
	ds_read_u16 v163, v141 offset:39632
	ds_read_u16 v164, v141 offset:40096
	ds_read_u16 v165, v141 offset:40160
	ds_read_u16 v166, v141 offset:40624
	ds_read_u16 v167, v141 offset:40688
	s_waitcnt lgkmcnt(0)
	v_lshlrev_b32_e32 v160, 16, v160
	v_lshlrev_b32_e32 v161, 16, v161
	v_mul_f32_e32 v192, v20, v160
	v_mul_f32_e32 v193, v4, v161
	v_mul_f32_e32 v113, v193, v193
	v_fmac_f32_e32 v113, v192, v192
	v_lshlrev_b32_e32 v162, 16, v162
	v_lshlrev_b32_e32 v163, 16, v163
	v_mul_f32_e32 v194, v21, v162
	v_mul_f32_e32 v195, v5, v163
	v_mul_f32_e32 v114, v195, v195
	v_fmac_f32_e32 v114, v194, v194
	v_lshlrev_b32_e32 v164, 16, v164
	v_lshlrev_b32_e32 v165, 16, v165
	v_mul_f32_e32 v196, v22, v164
	v_mul_f32_e32 v197, v6, v165
	v_mul_f32_e32 v115, v197, v197
	v_fmac_f32_e32 v115, v196, v196
	v_lshlrev_b32_e32 v166, 16, v166
	v_lshlrev_b32_e32 v167, 16, v167
	v_mul_f32_e32 v198, v23, v166
	v_mul_f32_e32 v199, v7, v167
	v_mul_f32_e32 v116, v199, v199
	v_fmac_f32_e32 v116, v198, v198
	ds_read_u16 v168, v141 offset:43264
	ds_read_u16 v169, v141 offset:43328
	ds_read_u16 v170, v141 offset:43792
	ds_read_u16 v171, v141 offset:43856
	ds_read_u16 v172, v141 offset:44320
	ds_read_u16 v173, v141 offset:44384
	ds_read_u16 v174, v141 offset:44848
	ds_read_u16 v175, v141 offset:44912
	s_waitcnt lgkmcnt(0)
	v_lshlrev_b32_e32 v168, 16, v168
	v_lshlrev_b32_e32 v169, 16, v169
	v_mul_f32_e32 v200, v24, v168
	v_mul_f32_e32 v201, v8, v169
	v_mul_f32_e32 v117, v201, v201
	v_fmac_f32_e32 v117, v200, v200
	v_lshlrev_b32_e32 v170, 16, v170
	v_lshlrev_b32_e32 v171, 16, v171
	v_mul_f32_e32 v202, v25, v170
	v_mul_f32_e32 v203, v9, v171
	v_mul_f32_e32 v118, v203, v203
	v_fmac_f32_e32 v118, v202, v202
	v_lshlrev_b32_e32 v172, 16, v172
	v_lshlrev_b32_e32 v173, 16, v173
	v_mul_f32_e32 v204, v26, v172
	v_mul_f32_e32 v205, v10, v173
	v_mul_f32_e32 v119, v205, v205
	v_fmac_f32_e32 v119, v204, v204
	v_lshlrev_b32_e32 v174, 16, v174
	v_lshlrev_b32_e32 v175, 16, v175
	v_mul_f32_e32 v206, v27, v174
	v_mul_f32_e32 v207, v11, v175
	v_mul_f32_e32 v120, v207, v207
	v_fmac_f32_e32 v120, v206, v206
	ds_read_u16 v176, v141 offset:47488
	ds_read_u16 v177, v141 offset:47552
	ds_read_u16 v178, v141 offset:48016
	ds_read_u16 v179, v141 offset:48080
	ds_read_u16 v180, v141 offset:48544
	ds_read_u16 v181, v141 offset:48608
	ds_read_u16 v182, v141 offset:49072
	ds_read_u16 v183, v141 offset:49136
	s_waitcnt lgkmcnt(0)
	v_lshlrev_b32_e32 v176, 16, v176
	v_lshlrev_b32_e32 v177, 16, v177
	v_mul_f32_e32 v208, v28, v176
	v_mul_f32_e32 v209, v12, v177
	v_mul_f32_e32 v121, v209, v209
	v_fmac_f32_e32 v121, v208, v208
	v_lshlrev_b32_e32 v178, 16, v178
	v_lshlrev_b32_e32 v179, 16, v179
	v_mul_f32_e32 v210, v29, v178
	v_mul_f32_e32 v211, v13, v179
	v_mul_f32_e32 v122, v211, v211
	v_fmac_f32_e32 v122, v210, v210
	v_lshlrev_b32_e32 v180, 16, v180
	v_lshlrev_b32_e32 v181, 16, v181
	v_mul_f32_e32 v212, v30, v180
	v_mul_f32_e32 v213, v14, v181
	v_mul_f32_e32 v123, v213, v213
	v_fmac_f32_e32 v123, v212, v212
	v_lshlrev_b32_e32 v182, 16, v182
	v_lshlrev_b32_e32 v183, 16, v183
	v_mul_f32_e32 v214, v31, v182
	v_mul_f32_e32 v215, v15, v183
	v_mul_f32_e32 v124, v215, v215
	v_fmac_f32_e32 v124, v214, v214
	ds_bpermute_b32 v125, v143, v109
	ds_bpermute_b32 v126, v143, v110
	ds_bpermute_b32 v127, v143, v111
	ds_bpermute_b32 v128, v143, v112
	ds_bpermute_b32 v129, v143, v113
	ds_bpermute_b32 v130, v143, v114
	ds_bpermute_b32 v131, v143, v115
	ds_bpermute_b32 v132, v143, v116
	s_waitcnt lgkmcnt(0)
	v_add_f32_e32 v109, v109, v125
	v_add_f32_e32 v110, v110, v126
	v_add_f32_e32 v111, v111, v127
	v_add_f32_e32 v112, v112, v128
	v_add_f32_e32 v113, v113, v129
	v_add_f32_e32 v114, v114, v130
	v_add_f32_e32 v115, v115, v131
	v_add_f32_e32 v116, v116, v132
	ds_bpermute_b32 v133, v143, v117
	ds_bpermute_b32 v134, v143, v118
	ds_bpermute_b32 v103, v143, v119
	ds_bpermute_b32 v104, v143, v120
	ds_bpermute_b32 v105, v143, v121
	ds_bpermute_b32 v106, v143, v122
	ds_bpermute_b32 v107, v143, v123
	ds_bpermute_b32 v100, v143, v124
	s_waitcnt lgkmcnt(0)
	v_add_f32_e32 v117, v117, v133
	v_add_f32_e32 v118, v118, v134
	v_add_f32_e32 v119, v119, v103
	v_add_f32_e32 v120, v120, v104
	v_add_f32_e32 v121, v121, v105
	v_add_f32_e32 v122, v122, v106
	v_add_f32_e32 v123, v123, v107
	v_add_f32_e32 v124, v124, v100
	ds_bpermute_b32 v125, v144, v109
	ds_bpermute_b32 v126, v144, v110
	ds_bpermute_b32 v127, v144, v111
	ds_bpermute_b32 v128, v144, v112
	ds_bpermute_b32 v129, v144, v113
	ds_bpermute_b32 v130, v144, v114
	ds_bpermute_b32 v131, v144, v115
	ds_bpermute_b32 v132, v144, v116
	s_waitcnt lgkmcnt(0)
	v_add_f32_e32 v109, v109, v125
	v_add_f32_e32 v110, v110, v126
	v_add_f32_e32 v111, v111, v127
	v_add_f32_e32 v112, v112, v128
	v_add_f32_e32 v113, v113, v129
	v_add_f32_e32 v114, v114, v130
	v_add_f32_e32 v115, v115, v131
	v_add_f32_e32 v116, v116, v132
	ds_bpermute_b32 v133, v144, v117
	ds_bpermute_b32 v134, v144, v118
	ds_bpermute_b32 v103, v144, v119
	ds_bpermute_b32 v104, v144, v120
	ds_bpermute_b32 v105, v144, v121
	ds_bpermute_b32 v106, v144, v122
	ds_bpermute_b32 v107, v144, v123
	ds_bpermute_b32 v100, v144, v124
	s_waitcnt lgkmcnt(0)
	v_add_f32_e32 v117, v117, v133
	v_add_f32_e32 v118, v118, v134
	v_add_f32_e32 v119, v119, v103
	v_add_f32_e32 v120, v120, v104
	v_add_f32_e32 v121, v121, v105
	v_add_f32_e32 v122, v122, v106
	v_add_f32_e32 v123, v123, v107
	v_add_f32_e32 v124, v124, v100
	ds_bpermute_b32 v125, v145, v109
	ds_bpermute_b32 v126, v145, v110
	ds_bpermute_b32 v127, v145, v111
	ds_bpermute_b32 v128, v145, v112
	ds_bpermute_b32 v129, v145, v113
	ds_bpermute_b32 v130, v145, v114
	ds_bpermute_b32 v131, v145, v115
	ds_bpermute_b32 v132, v145, v116
	s_waitcnt lgkmcnt(0)
	v_add_f32_e32 v109, v109, v125
	v_add_f32_e32 v110, v110, v126
	v_add_f32_e32 v111, v111, v127
	v_add_f32_e32 v112, v112, v128
	v_add_f32_e32 v113, v113, v129
	v_add_f32_e32 v114, v114, v130
	v_add_f32_e32 v115, v115, v131
	v_add_f32_e32 v116, v116, v132
	ds_bpermute_b32 v133, v145, v117
	ds_bpermute_b32 v134, v145, v118
	ds_bpermute_b32 v103, v145, v119
	ds_bpermute_b32 v104, v145, v120
	ds_bpermute_b32 v105, v145, v121
	ds_bpermute_b32 v106, v145, v122
	ds_bpermute_b32 v107, v145, v123
	ds_bpermute_b32 v100, v145, v124
	s_waitcnt lgkmcnt(0)
	v_add_f32_e32 v117, v117, v133
	v_add_f32_e32 v118, v118, v134
	v_add_f32_e32 v119, v119, v103
	v_add_f32_e32 v120, v120, v104
	v_add_f32_e32 v121, v121, v105
	v_add_f32_e32 v122, v122, v106
	v_add_f32_e32 v123, v123, v107
	v_add_f32_e32 v124, v124, v100
	ds_bpermute_b32 v125, v146, v109
	ds_bpermute_b32 v126, v146, v110
	ds_bpermute_b32 v127, v146, v111
	ds_bpermute_b32 v128, v146, v112
	ds_bpermute_b32 v129, v146, v113
	ds_bpermute_b32 v130, v146, v114
	ds_bpermute_b32 v131, v146, v115
	ds_bpermute_b32 v132, v146, v116
	s_waitcnt lgkmcnt(0)
	v_add_f32_e32 v109, v109, v125
	v_add_f32_e32 v110, v110, v126
	v_add_f32_e32 v111, v111, v127
	v_add_f32_e32 v112, v112, v128
	v_add_f32_e32 v113, v113, v129
	v_add_f32_e32 v114, v114, v130
	v_add_f32_e32 v115, v115, v131
	v_add_f32_e32 v116, v116, v132
	ds_bpermute_b32 v133, v146, v117
	ds_bpermute_b32 v134, v146, v118
	ds_bpermute_b32 v103, v146, v119
	ds_bpermute_b32 v104, v146, v120
	ds_bpermute_b32 v105, v146, v121
	ds_bpermute_b32 v106, v146, v122
	ds_bpermute_b32 v107, v146, v123
	ds_bpermute_b32 v100, v146, v124
	s_waitcnt lgkmcnt(0)
	v_add_f32_e32 v117, v117, v133
	v_add_f32_e32 v118, v118, v134
	v_add_f32_e32 v119, v119, v103
	v_add_f32_e32 v120, v120, v104
	v_add_f32_e32 v121, v121, v105
	v_add_f32_e32 v122, v122, v106
	v_add_f32_e32 v123, v123, v107
	v_add_f32_e32 v124, v124, v100
	ds_bpermute_b32 v125, v147, v109
	ds_bpermute_b32 v126, v147, v110
	ds_bpermute_b32 v127, v147, v111
	ds_bpermute_b32 v128, v147, v112
	ds_bpermute_b32 v129, v147, v113
	ds_bpermute_b32 v130, v147, v114
	ds_bpermute_b32 v131, v147, v115
	ds_bpermute_b32 v132, v147, v116
	s_waitcnt lgkmcnt(0)
	v_add_f32_e32 v109, v109, v125
	v_add_f32_e32 v110, v110, v126
	v_add_f32_e32 v111, v111, v127
	v_add_f32_e32 v112, v112, v128
	v_add_f32_e32 v113, v113, v129
	v_add_f32_e32 v114, v114, v130
	v_add_f32_e32 v115, v115, v131
	v_add_f32_e32 v116, v116, v132
	ds_bpermute_b32 v133, v147, v117
	ds_bpermute_b32 v134, v147, v118
	ds_bpermute_b32 v103, v147, v119
	ds_bpermute_b32 v104, v147, v120
	ds_bpermute_b32 v105, v147, v121
	ds_bpermute_b32 v106, v147, v122
	ds_bpermute_b32 v107, v147, v123
	ds_bpermute_b32 v100, v147, v124
	s_waitcnt lgkmcnt(0)
	v_add_f32_e32 v117, v117, v133
	v_add_f32_e32 v118, v118, v134
	v_add_f32_e32 v119, v119, v103
	v_add_f32_e32 v120, v120, v104
	v_add_f32_e32 v121, v121, v105
	v_add_f32_e32 v122, v122, v106
	v_add_f32_e32 v123, v123, v107
	v_add_f32_e32 v124, v124, v100
	v_cmp_eq_u32_e32 vcc, 0, v40
	s_and_saveexec_b64 s[0:1], vcc
	ds_write_b32 v151, v109 offset:51712
	ds_write_b32 v151, v110 offset:51716
	ds_write_b32 v151, v111 offset:51720
	ds_write_b32 v151, v112 offset:51724
	ds_write_b32 v151, v113 offset:51744
	ds_write_b32 v151, v114 offset:51748
	ds_write_b32 v151, v115 offset:51752
	ds_write_b32 v151, v116 offset:51756
	ds_write_b32 v151, v117 offset:51776
	ds_write_b32 v151, v118 offset:51780
	ds_write_b32 v151, v119 offset:51784
	ds_write_b32 v151, v120 offset:51788
	ds_write_b32 v151, v121 offset:51808
	ds_write_b32 v151, v122 offset:51812
	ds_write_b32 v151, v123 offset:51816
	ds_write_b32 v151, v124 offset:51820
	s_or_b64 exec, exec, s[0:1]
	v_mov_b32_e32 v67, v184
	v_mov_b32_e32 v66, v185
	v_mov_b32_e32 v65, v186
	v_mov_b32_e32 v63, v187
	v_mov_b32_e32 v60, v188
	v_mov_b32_e32 v59, v189
	v_mov_b32_e32 v64, v190
	v_mov_b32_e32 v61, v191
	v_mov_b32_e32 v51, v192
	v_mov_b32_e32 v49, v193
	v_mov_b32_e32 v52, v194
	v_mov_b32_e32 v50, v195
	v_mov_b32_e32 v47, v196
	v_mov_b32_e32 v45, v197
	v_mov_b32_e32 v48, v198
	v_mov_b32_e32 v46, v199
	v_mov_b32_e32 v43, v200
	v_mov_b32_e32 v42, v201
	v_mov_b32_e32 v54, v202
	v_mov_b32_e32 v53, v203
	v_mov_b32_e32 v56, v204
	v_mov_b32_e32 v55, v205
	v_mov_b32_e32 v58, v206
	v_mov_b32_e32 v57, v207
	v_mov_b32_e32 v40, v208
	v_mov_b32_e32 v38, v209
	v_mov_b32_e32 v41, v210
	v_mov_b32_e32 v39, v211
	v_mov_b32_e32 v36, v212
	v_mov_b32_e32 v30, v213
	v_mov_b32_e32 v37, v214
	v_mov_b32_e32 v31, v215
	v_mov_b32_e32 v0, v149
	v_or_b32_e32 v62, 1, v149
	s_waitcnt lgkmcnt(0)
	s_branch .LBB0_1473
